# P4->P5 barrier becomes XCD-local (no cross-XCD stage, no L2 flush) when the placement check passed: H panels are produced and consumed on one XCD, so XCDs run P4/P5 independently
# speedup vs baseline: 1.0059x; 1.0021x over previous
; __device__ __forceinline__ unsigned xb_add(unsigned* p, unsigned v) { return __hip_atomic_fetch_add(p, v, __ATOMIC_RELAXED, __HIP_MEMORY_SCOPE_AGENT); }
; __device__ __forceinline__ void xcd_barrier(const XcdBarrier& b) {
;     ...
;             __builtin_amdgcn_fence(__ATOMIC_ACQUIRE, "agent");
;             xb_add(&bar[XB_XGEN(b.x)], 1u);
;             asm volatile("s_waitcnt vmcnt(0)" ::: "memory");
.Lxcd_local_rel:
	s_waitcnt vmcnt(0)
	s_cmp_eq_u32 s32, 0
	s_cbranch_scc1 .Lh_local_0
	buffer_inv sc1
